# v14 + P0 S5-ZOH loop: 32 b_re/b_im loads issued together (one wait) instead of 16 serial load-pair round trips
# speedup vs baseline: 1.0030x; 1.0030x over previous
.LBB0_77:
	s_or_b64 exec, exec, s[2:3]
	s_waitcnt vmcnt(0)
	v_cvt_f64_f32_e32 v[62:63], v20
	v_min_f64 v[70:71], v[62:63], s[76:77]
	v_mul_f64 v[60:61], v[70:71], v[60:61]
	v_mul_f64 v[62:63], v[60:61], s[52:53]
	v_rndne_f64_e32 v[62:63], v[62:63]
	v_fmac_f64_e32 v[60:61], s[54:55], v[62:63]
	v_fmac_f64_e32 v[60:61], s[84:85], v[62:63]
	v_mov_b64_e32 v[72:73], v[50:51]
	v_fmac_f64_e32 v[72:73], s[88:89], v[60:61]
	v_mov_b64_e32 v[74:75], v[14:15]
	v_fmac_f64_e32 v[74:75], v[72:73], v[60:61]
	v_mov_b64_e32 v[72:73], v[16:17]
	v_fmac_f64_e32 v[72:73], v[74:75], v[60:61]
	v_mov_b64_e32 v[74:75], v[52:53]
	v_fmac_f64_e32 v[74:75], v[72:73], v[60:61]
	v_mov_b64_e32 v[72:73], v[18:19]
	v_mov_b32_e32 v20, v18
	v_fmac_f64_e32 v[72:73], v[74:75], v[60:61]
	v_mov_b64_e32 v[74:75], v[20:21]
	v_fmac_f64_e32 v[74:75], v[72:73], v[60:61]
	v_mov_b64_e32 v[72:73], v[24:25]
	v_fmac_f64_e32 v[72:73], v[74:75], v[60:61]
	v_mov_b64_e32 v[74:75], v[54:55]
	v_fmac_f64_e32 v[74:75], v[72:73], v[60:61]
	v_mov_b64_e32 v[72:73], v[26:27]
	v_mov_b32_e32 v28, v26
	v_fmac_f64_e32 v[72:73], v[74:75], v[60:61]
	v_mov_b64_e32 v[74:75], v[28:29]
	v_fmac_f64_e32 v[74:75], v[72:73], v[60:61]
	v_fma_f64 v[72:73], v[74:75], v[60:61], 0.5
	v_fma_f64 v[72:73], v[72:73], v[60:61], 1.0
	v_fma_f64 v[60:61], v[72:73], v[60:61], 1.0
	v_ldexp_f64 v[72:73], v[62:63], s33
	v_floor_f64_e32 v[72:73], v[72:73]
	v_fmac_f64_e32 v[62:63], 0xc1f00000, v[72:73]
	v_cvt_u32_f64_e32 v20, v[62:63]
	v_lshl_add_u32 v33, v20, 20, v1
	v_xor_b32_e32 v20, 0x80000000, v59
	v_cmp_gt_f32_e32 vcc, 0, v69
	v_mul_f64 v[72:73], v[60:61], v[32:33]
	v_mul_f64 v[62:63], v[72:73], v[66:67]
	v_cndmask_b32_e32 v59, v59, v20, vcc
	v_mul_f64 v[74:75], v[72:73], v[58:59]
	v_lshl_add_u64 v[60:61], s[70:71], 0, v[6:7]
	v_cvt_f32_f64_e32 v59, v[74:75]
	v_cvt_f32_f64_e32 v58, v[62:63]
	global_store_dwordx2 v[60:61], v[58:59], off
	v_lshl_add_u64 v[62:63], s[64:65], 0, v[10:11]
	v_lshl_add_u64 v[60:61], s[62:63], 0, v[10:11]
	global_load_dword v28, v[62:63], off
	global_load_dword v20, v[60:61], off
	global_load_dword v101, v[60:61], off offset:4
	global_load_dword v117, v[62:63], off offset:4
	global_load_dword v102, v[60:61], off offset:8
	global_load_dword v118, v[62:63], off offset:8
	global_load_dword v103, v[60:61], off offset:12
	global_load_dword v119, v[62:63], off offset:12
	global_load_dword v104, v[60:61], off offset:16
	global_load_dword v120, v[62:63], off offset:16
	global_load_dword v105, v[60:61], off offset:20
	global_load_dword v121, v[62:63], off offset:20
	global_load_dword v106, v[60:61], off offset:24
	global_load_dword v122, v[62:63], off offset:24
	global_load_dword v107, v[60:61], off offset:28
	global_load_dword v123, v[62:63], off offset:28
	global_load_dword v108, v[60:61], off offset:32
	global_load_dword v124, v[62:63], off offset:32
	global_load_dword v109, v[60:61], off offset:36
	global_load_dword v125, v[62:63], off offset:36
	global_load_dword v110, v[60:61], off offset:40
	global_load_dword v126, v[62:63], off offset:40
	global_load_dword v111, v[60:61], off offset:44
	global_load_dword v127, v[62:63], off offset:44
	global_load_dword v112, v[60:61], off offset:48
	global_load_dword v128, v[62:63], off offset:48
	global_load_dword v113, v[60:61], off offset:52
	global_load_dword v129, v[62:63], off offset:52
	global_load_dword v114, v[60:61], off offset:56
	global_load_dword v130, v[62:63], off offset:56
	global_load_dword v115, v[60:61], off offset:60
	global_load_dword v131, v[62:63], off offset:60
	v_fma_f64 v[66:67], v[72:73], v[66:67], -1.0
	v_mul_f64 v[76:77], v[64:65], v[64:65]
	v_mul_f64 v[72:73], v[70:71], v[66:67]
	v_lshl_add_u64 v[58:59], s[70:71], 0, v[8:9]
	s_mov_b32 s2, 0x308000
	v_fmac_f64_e32 v[76:77], v[70:71], v[70:71]
	v_mul_f64 v[66:67], v[66:67], v[64:65]
	v_fmac_f64_e32 v[72:73], v[74:75], v[64:65]
	v_add_co_u32_e32 v58, vcc, s2, v58
	v_fma_f64 v[66:67], v[70:71], v[74:75], -v[66:67]
	v_div_scale_f64 v[64:65], s[2:3], v[76:77], v[76:77], v[72:73]
	v_div_scale_f64 v[74:75], s[2:3], v[76:77], v[76:77], v[66:67]
	v_rcp_f64_e32 v[78:79], v[64:65]
	v_rcp_f64_e32 v[80:81], v[74:75]
	v_addc_co_u32_e32 v59, vcc, 0, v59, vcc
	v_fma_f64 v[84:85], -v[64:65], v[78:79], 1.0
	v_fma_f64 v[86:87], -v[74:75], v[80:81], 1.0
	v_fmac_f64_e32 v[78:79], v[78:79], v[84:85]
	v_fmac_f64_e32 v[80:81], v[80:81], v[86:87]
	v_fma_f64 v[84:85], -v[64:65], v[78:79], 1.0
	v_div_scale_f64 v[70:71], vcc, v[72:73], v[76:77], v[72:73]
	v_fma_f64 v[86:87], -v[74:75], v[80:81], 1.0
	v_fmac_f64_e32 v[78:79], v[78:79], v[84:85]
	v_div_scale_f64 v[82:83], s[2:3], v[66:67], v[76:77], v[66:67]
	v_fmac_f64_e32 v[80:81], v[80:81], v[86:87]
	v_mul_f64 v[84:85], v[70:71], v[78:79]
	v_mul_f64 v[86:87], v[82:83], v[80:81]
	v_fma_f64 v[64:65], -v[64:65], v[84:85], v[70:71]
	v_fma_f64 v[70:71], -v[74:75], v[86:87], v[82:83]
	v_div_fmas_f64 v[64:65], v[64:65], v[78:79], v[84:85]
	s_mov_b64 vcc, s[2:3]
	v_div_fmas_f64 v[70:71], v[70:71], v[80:81], v[86:87]
	v_div_fixup_f64 v[64:65], v[64:65], v[76:77], v[72:73]
	v_div_fixup_f64 v[66:67], v[70:71], v[76:77], v[66:67]
	v_lshl_add_u64 v[56:57], v[56:57], 0, s[6:7]
	s_mov_b64 s[2:3], 0xfff
	v_cmp_lt_u64_e32 vcc, s[2:3], v[56:57]
	v_lshl_add_u64 v[4:5], v[4:5], 0, s[10:11]
	v_lshl_add_u64 v[6:7], v[6:7], 0, s[40:41]
	v_lshl_add_u64 v[8:9], v[8:9], 0, s[42:43]
	s_or_b64 s[44:45], vcc, s[44:45]
	v_lshl_add_u64 v[10:11], v[10:11], 0, s[50:51]
	s_waitcnt vmcnt(0)
	v_cvt_f64_f32_e32 v[72:73], v28
	s_waitcnt vmcnt(0)
	v_cvt_f64_f32_e32 v[70:71], v20
	v_mul_f64 v[74:75], v[66:67], v[72:73]
	v_mul_f64 v[72:73], v[64:65], v[72:73]
	v_fma_f64 v[74:75], v[64:65], v[70:71], -v[74:75]
	v_fmac_f64_e32 v[72:73], v[66:67], v[70:71]
	v_cvt_f32_f64_e32 v20, v[74:75]
	v_cvt_f32_f64_e32 v28, v[72:73]
	global_store_dword v[58:59], v20, off
	global_store_dword v[58:59], v28, off offset:64
	s_nop 0
	v_cvt_f64_f32_e32 v[70:71], v101
	v_cvt_f64_f32_e32 v[72:73], v117
	v_mul_f64 v[74:75], v[66:67], v[72:73]
	v_mul_f64 v[72:73], v[64:65], v[72:73]
	v_fma_f64 v[74:75], v[64:65], v[70:71], -v[74:75]
	v_fmac_f64_e32 v[72:73], v[66:67], v[70:71]
	v_cvt_f32_f64_e32 v20, v[74:75]
	v_cvt_f32_f64_e32 v28, v[72:73]
	global_store_dword v[58:59], v20, off offset:4
	global_store_dword v[58:59], v28, off offset:68
	s_nop 0
	v_cvt_f64_f32_e32 v[70:71], v102
	v_cvt_f64_f32_e32 v[72:73], v118
	v_mul_f64 v[74:75], v[66:67], v[72:73]
	v_mul_f64 v[72:73], v[64:65], v[72:73]
	v_fma_f64 v[74:75], v[64:65], v[70:71], -v[74:75]
	v_fmac_f64_e32 v[72:73], v[66:67], v[70:71]
	v_cvt_f32_f64_e32 v20, v[74:75]
	v_cvt_f32_f64_e32 v28, v[72:73]
	global_store_dword v[58:59], v20, off offset:8
	global_store_dword v[58:59], v28, off offset:72
	s_nop 0
	v_cvt_f64_f32_e32 v[70:71], v103
	v_cvt_f64_f32_e32 v[72:73], v119
	v_mul_f64 v[74:75], v[66:67], v[72:73]
	v_mul_f64 v[72:73], v[64:65], v[72:73]
	v_fma_f64 v[74:75], v[64:65], v[70:71], -v[74:75]
	v_fmac_f64_e32 v[72:73], v[66:67], v[70:71]
	v_cvt_f32_f64_e32 v20, v[74:75]
	v_cvt_f32_f64_e32 v28, v[72:73]
	global_store_dword v[58:59], v20, off offset:12
	global_store_dword v[58:59], v28, off offset:76
	s_nop 0
	v_cvt_f64_f32_e32 v[70:71], v104
	v_cvt_f64_f32_e32 v[72:73], v120
	v_mul_f64 v[74:75], v[66:67], v[72:73]
	v_mul_f64 v[72:73], v[64:65], v[72:73]
	v_fma_f64 v[74:75], v[64:65], v[70:71], -v[74:75]
	v_fmac_f64_e32 v[72:73], v[66:67], v[70:71]
	v_cvt_f32_f64_e32 v20, v[74:75]
	v_cvt_f32_f64_e32 v28, v[72:73]
	global_store_dword v[58:59], v20, off offset:16
	global_store_dword v[58:59], v28, off offset:80
	s_nop 0
	v_cvt_f64_f32_e32 v[70:71], v105
	v_cvt_f64_f32_e32 v[72:73], v121
	v_mul_f64 v[74:75], v[66:67], v[72:73]
	v_mul_f64 v[72:73], v[64:65], v[72:73]
	v_fma_f64 v[74:75], v[64:65], v[70:71], -v[74:75]
	v_fmac_f64_e32 v[72:73], v[66:67], v[70:71]
	v_cvt_f32_f64_e32 v20, v[74:75]
	v_cvt_f32_f64_e32 v28, v[72:73]
	global_store_dword v[58:59], v20, off offset:20
	global_store_dword v[58:59], v28, off offset:84
	s_nop 0
	v_cvt_f64_f32_e32 v[70:71], v106
	v_cvt_f64_f32_e32 v[72:73], v122
	v_mul_f64 v[74:75], v[66:67], v[72:73]
	v_mul_f64 v[72:73], v[64:65], v[72:73]
	v_fma_f64 v[74:75], v[64:65], v[70:71], -v[74:75]
	v_fmac_f64_e32 v[72:73], v[66:67], v[70:71]
	v_cvt_f32_f64_e32 v20, v[74:75]
	v_cvt_f32_f64_e32 v28, v[72:73]
	global_store_dword v[58:59], v20, off offset:24
	global_store_dword v[58:59], v28, off offset:88
	s_nop 0
	v_cvt_f64_f32_e32 v[70:71], v107
	v_cvt_f64_f32_e32 v[72:73], v123
	v_mul_f64 v[74:75], v[66:67], v[72:73]
	v_mul_f64 v[72:73], v[64:65], v[72:73]
	v_fma_f64 v[74:75], v[64:65], v[70:71], -v[74:75]
	v_fmac_f64_e32 v[72:73], v[66:67], v[70:71]
	v_cvt_f32_f64_e32 v20, v[74:75]
	v_cvt_f32_f64_e32 v28, v[72:73]
	global_store_dword v[58:59], v20, off offset:28
	global_store_dword v[58:59], v28, off offset:92
	s_nop 0
	v_cvt_f64_f32_e32 v[70:71], v108
	v_cvt_f64_f32_e32 v[72:73], v124
	v_mul_f64 v[74:75], v[66:67], v[72:73]
	v_mul_f64 v[72:73], v[64:65], v[72:73]
	v_fma_f64 v[74:75], v[64:65], v[70:71], -v[74:75]
	v_fmac_f64_e32 v[72:73], v[66:67], v[70:71]
	v_cvt_f32_f64_e32 v20, v[74:75]
	v_cvt_f32_f64_e32 v28, v[72:73]
	global_store_dword v[58:59], v20, off offset:32
	global_store_dword v[58:59], v28, off offset:96
	s_nop 0
	v_cvt_f64_f32_e32 v[70:71], v109
	v_cvt_f64_f32_e32 v[72:73], v125
	v_mul_f64 v[74:75], v[66:67], v[72:73]
	v_mul_f64 v[72:73], v[64:65], v[72:73]
	v_fma_f64 v[74:75], v[64:65], v[70:71], -v[74:75]
	v_fmac_f64_e32 v[72:73], v[66:67], v[70:71]
	v_cvt_f32_f64_e32 v20, v[74:75]
	v_cvt_f32_f64_e32 v28, v[72:73]
	global_store_dword v[58:59], v20, off offset:36
	global_store_dword v[58:59], v28, off offset:100
	s_nop 0
	v_cvt_f64_f32_e32 v[70:71], v110
	v_cvt_f64_f32_e32 v[72:73], v126
	v_mul_f64 v[74:75], v[66:67], v[72:73]
	v_mul_f64 v[72:73], v[64:65], v[72:73]
	v_fma_f64 v[74:75], v[64:65], v[70:71], -v[74:75]
	v_fmac_f64_e32 v[72:73], v[66:67], v[70:71]
	v_cvt_f32_f64_e32 v20, v[74:75]
	v_cvt_f32_f64_e32 v28, v[72:73]
	global_store_dword v[58:59], v20, off offset:40
	global_store_dword v[58:59], v28, off offset:104
	s_nop 0
	v_cvt_f64_f32_e32 v[70:71], v111
	v_cvt_f64_f32_e32 v[72:73], v127
	v_mul_f64 v[74:75], v[66:67], v[72:73]
	v_mul_f64 v[72:73], v[64:65], v[72:73]
	v_fma_f64 v[74:75], v[64:65], v[70:71], -v[74:75]
	v_fmac_f64_e32 v[72:73], v[66:67], v[70:71]
	v_cvt_f32_f64_e32 v20, v[74:75]
	v_cvt_f32_f64_e32 v28, v[72:73]
	global_store_dword v[58:59], v20, off offset:44
	global_store_dword v[58:59], v28, off offset:108
	s_nop 0
	v_cvt_f64_f32_e32 v[70:71], v112
	v_cvt_f64_f32_e32 v[72:73], v128
	v_mul_f64 v[74:75], v[66:67], v[72:73]
	v_mul_f64 v[72:73], v[64:65], v[72:73]
	v_fma_f64 v[74:75], v[64:65], v[70:71], -v[74:75]
	v_fmac_f64_e32 v[72:73], v[66:67], v[70:71]
	v_cvt_f32_f64_e32 v20, v[74:75]
	v_cvt_f32_f64_e32 v28, v[72:73]
	global_store_dword v[58:59], v20, off offset:48
	global_store_dword v[58:59], v28, off offset:112
	s_nop 0
	v_cvt_f64_f32_e32 v[70:71], v113
	v_cvt_f64_f32_e32 v[72:73], v129
	v_mul_f64 v[74:75], v[66:67], v[72:73]
	v_mul_f64 v[72:73], v[64:65], v[72:73]
	v_fma_f64 v[74:75], v[64:65], v[70:71], -v[74:75]
	v_fmac_f64_e32 v[72:73], v[66:67], v[70:71]
	v_cvt_f32_f64_e32 v20, v[74:75]
	v_cvt_f32_f64_e32 v28, v[72:73]
	global_store_dword v[58:59], v20, off offset:52
	global_store_dword v[58:59], v28, off offset:116
	s_nop 0
	v_cvt_f64_f32_e32 v[70:71], v114
	v_cvt_f64_f32_e32 v[72:73], v130
	v_mul_f64 v[74:75], v[66:67], v[72:73]
	v_mul_f64 v[72:73], v[64:65], v[72:73]
	v_fma_f64 v[74:75], v[64:65], v[70:71], -v[74:75]
	v_fmac_f64_e32 v[72:73], v[66:67], v[70:71]
	v_cvt_f32_f64_e32 v20, v[74:75]
	v_cvt_f32_f64_e32 v28, v[72:73]
	global_store_dword v[58:59], v20, off offset:56
	global_store_dword v[58:59], v28, off offset:120
	s_nop 0
	v_cvt_f64_f32_e32 v[60:61], v115
	v_cvt_f64_f32_e32 v[62:63], v131
	v_mul_f64 v[70:71], v[66:67], v[62:63]
	v_mul_f64 v[62:63], v[64:65], v[62:63]
	v_fma_f64 v[64:65], v[64:65], v[60:61], -v[70:71]
	v_fmac_f64_e32 v[62:63], v[66:67], v[60:61]
	v_cvt_f32_f64_e32 v20, v[64:65]
	v_cvt_f32_f64_e32 v28, v[62:63]
	global_store_dword v[58:59], v20, off offset:60
	global_store_dword v[58:59], v28, off offset:124
	s_andn2_b64 exec, exec, s[44:45]
	s_cbranch_execz .LBB0_83
